# streaming (nt) hint on the single-use gate-row loads of the attention epilogue
# baseline (speedup 1.0000x reference)
.Ltk_skip0:
	s_waitcnt lgkmcnt(0)
	ds_read_b128 v[32:35], v216 offset:49280
	ds_read_b128 v[36:39], v216 offset:49312
	s_lshl_b64 s[2:3], s[2:3], 12
	v_readlane_b32 s4, v252, 37
	s_add_u32 s5, s4, s2
	s_waitcnt lgkmcnt(1)
	v_rcp_f32_e32 v40, v32
	v_readlane_b32 s2, v252, 38
	s_addc_u32 s6, s2, s3
	s_lshl_b64 s[2:3], s[14:15], 1
	v_readlane_b32 s4, v252, 35
	v_rcp_f32_e32 v41, v33
	s_add_u32 s7, s4, s2
	v_readlane_b32 s2, v252, 36
	s_addc_u32 s14, s2, s3
	s_add_u32 s100, s7, s12
	s_addc_u32 s101, s14, 0
	v_lshlrev_b32_e32 v50, 1, v210
	v_and_b32_e32 v50, 0x70, v50
	v_mov_b32_e32 v51, 0
	v_lshrrev_b32_e32 v52, 3, v197
	v_lshl_add_u64 v[66:67], s[100:101], 0, v[50:51]
	v_or_b32_e32 v50, 0, v52
	v_lshlrev_b32_e32 v50, 11, v50
	v_lshl_add_u64 v[68:69], v[66:67], 0, v[50:51]
	global_load_dwordx4 v[70:73], v[68:69], off nt
	v_or_b32_e32 v50, 8, v52
	v_lshlrev_b32_e32 v50, 11, v50
	v_lshl_add_u64 v[68:69], v[66:67], 0, v[50:51]
	global_load_dwordx4 v[74:77], v[68:69], off nt
	v_or_b32_e32 v50, 16, v52
	v_lshlrev_b32_e32 v50, 11, v50
	v_lshl_add_u64 v[68:69], v[66:67], 0, v[50:51]
	global_load_dwordx4 v[78:81], v[68:69], off nt
	v_or_b32_e32 v50, 24, v52
	v_lshlrev_b32_e32 v50, 11, v50
	v_lshl_add_u64 v[68:69], v[66:67], 0, v[50:51]
	global_load_dwordx4 v[82:85], v[68:69], off nt
	s_lshl_b32 s2, s13, 12
	s_add_i32 s4, s2, 0
	v_lshlrev_b32_e32 v48, 1, v211
	v_lshlrev_b32_e32 v49, 9, v212
	v_mul_f32_e32 v0, v0, v40
	v_add3_u32 v48, s4, v48, v49
	v_cvt_pk_bf16_f32 v0, v0, s0
	v_rcp_f32_e32 v42, v34
	v_rcp_f32_e32 v43, v35
	s_waitcnt lgkmcnt(0)
	v_rcp_f32_e32 v44, v36
	ds_read_b128 v[32:35], v216 offset:49344
	v_rcp_f32_e32 v45, v37
	v_rcp_f32_e32 v46, v38
	v_rcp_f32_e32 v47, v39
	ds_read_b128 v[36:39], v216 offset:49376
	ds_write_b16 v48, v0 offset:51264
	v_mul_f32_e32 v0, v17, v41
	v_cvt_pk_bf16_f32 v0, v0, s0
	ds_write_b16 v48, v0 offset:51328
	v_mul_f32_e32 v0, v1, v41
	v_cvt_pk_bf16_f32 v0, v0, s0
	ds_write_b16 v48, v0 offset:51392
	v_mul_f32_e32 v0, v18, v42
	v_cvt_pk_bf16_f32 v0, v0, s0
	ds_write_b16 v48, v0 offset:51456
	v_mul_f32_e32 v0, v2, v42
	v_cvt_pk_bf16_f32 v0, v0, s0
	ds_write_b16 v48, v0 offset:51520
	v_mul_f32_e32 v0, v19, v43
	v_cvt_pk_bf16_f32 v0, v0, s0
	ds_write_b16 v48, v0 offset:51584
	v_mul_f32_e32 v0, v3, v43
	v_cvt_pk_bf16_f32 v0, v0, s0
	ds_write_b16 v48, v0 offset:51648
	v_mul_f32_e32 v0, v20, v44
	v_cvt_pk_bf16_f32 v0, v0, s0
	ds_write_b16 v48, v0 offset:52224
	v_mul_f32_e32 v0, v4, v44
	v_cvt_pk_bf16_f32 v0, v0, s0
	ds_write_b16 v48, v0 offset:52288
	v_mul_f32_e32 v0, v21, v45
	v_cvt_pk_bf16_f32 v0, v0, s0
	ds_write_b16 v48, v0 offset:52352
	v_mul_f32_e32 v0, v5, v45
	v_cvt_pk_bf16_f32 v0, v0, s0
	ds_write_b16 v48, v0 offset:52416
	v_mul_f32_e32 v0, v22, v46
	v_cvt_pk_bf16_f32 v0, v0, s0
	ds_write_b16 v48, v0 offset:52480
	v_mul_f32_e32 v0, v6, v46
	v_cvt_pk_bf16_f32 v0, v0, s0
	s_waitcnt lgkmcnt(13)
	v_rcp_f32_e32 v32, v32
	ds_write_b16 v48, v0 offset:52544
	v_mul_f32_e32 v0, v23, v47
	v_cvt_pk_bf16_f32 v0, v0, s0
	ds_write_b16 v48, v0 offset:52608
	v_mul_f32_e32 v0, v7, v47
	v_cvt_pk_bf16_f32 v0, v0, s0
	v_rcp_f32_e32 v33, v33
	ds_write_b16 v48, v0 offset:52672
	v_mul_f32_e32 v0, v24, v32
	v_cvt_pk_bf16_f32 v0, v0, s0
	ds_write_b16 v48, v0 offset:53248
	v_mul_f32_e32 v0, v8, v32
	v_cvt_pk_bf16_f32 v0, v0, s0
	v_rcp_f32_e32 v34, v34
	ds_write_b16 v48, v0 offset:53312
	v_mul_f32_e32 v0, v25, v33
	v_cvt_pk_bf16_f32 v0, v0, s0
	ds_write_b16 v48, v0 offset:53376
	v_mul_f32_e32 v0, v9, v33
	v_cvt_pk_bf16_f32 v0, v0, s0
	v_rcp_f32_e32 v35, v35
	ds_write_b16 v48, v0 offset:53440
	v_mul_f32_e32 v0, v26, v34
	v_cvt_pk_bf16_f32 v0, v0, s0
	ds_write_b16 v48, v0 offset:53504
	v_mul_f32_e32 v0, v10, v34
	v_cvt_pk_bf16_f32 v0, v0, s0
	s_waitcnt lgkmcnt(14)
	v_rcp_f32_e32 v36, v36
	ds_write_b16 v48, v0 offset:53568
	v_mul_f32_e32 v0, v27, v35
	v_cvt_pk_bf16_f32 v0, v0, s0
	ds_write_b16 v48, v0 offset:53632
	v_mul_f32_e32 v0, v11, v35
	v_cvt_pk_bf16_f32 v0, v0, s0
	v_rcp_f32_e32 v37, v37
	ds_write_b16 v48, v0 offset:53696
	v_mul_f32_e32 v0, v28, v36
	v_cvt_pk_bf16_f32 v0, v0, s0
	ds_write_b16 v48, v0 offset:54272
	v_mul_f32_e32 v0, v12, v36
	v_cvt_pk_bf16_f32 v0, v0, s0
	v_rcp_f32_e32 v38, v38
	ds_write_b16 v48, v0 offset:54336
	v_mul_f32_e32 v0, v29, v37
	v_cvt_pk_bf16_f32 v0, v0, s0
	ds_write_b16 v48, v0 offset:54400
	v_mul_f32_e32 v0, v13, v37
	v_cvt_pk_bf16_f32 v0, v0, s0
	v_rcp_f32_e32 v39, v39
	ds_write_b16 v48, v0 offset:54464
	v_mul_f32_e32 v0, v30, v38
	v_cvt_pk_bf16_f32 v0, v0, s0
	ds_write_b16 v48, v0 offset:54528
	v_mul_f32_e32 v0, v14, v38
	v_cvt_pk_bf16_f32 v0, v0, s0
	ds_write_b16 v48, v0 offset:54592
	v_mul_f32_e32 v0, v31, v39
	v_cvt_pk_bf16_f32 v0, v0, s0
	ds_write_b16 v48, v0 offset:54656
	v_mul_f32_e32 v0, v15, v39
	s_add_u32 s2, s5, s12
	v_mul_f32_e32 v16, v16, v40
	v_cvt_pk_bf16_f32 v0, v0, s0
	s_addc_u32 s3, s6, 0
	v_cvt_pk_bf16_f32 v16, v16, s0
	ds_write_b16 v48, v0 offset:54720
	s_add_u32 s6, s7, s12
	v_lshlrev_b32_e32 v0, 1, v210
	ds_write_b16 v48, v16 offset:51200
	s_addc_u32 s7, s14, 0
	v_lshrrev_b32_e32 v24, 3, v197
	v_and_b32_e32 v16, 0x70, v0
	v_mov_b32_e32 v17, v193
	v_lshl_add_u64 v[18:19], s[6:7], 0, v[16:17]
	v_lshlrev_b32_e32 v0, 11, v24
	v_mov_b32_e32 v1, v193
	s_waitcnt lgkmcnt(0)
	v_lshl_add_u64 v[0:1], v[18:19], 0, v[0:1]
	global_load_dwordx4 v[0:3], v[0:1], off nt
	v_or_b32_e32 v25, 8, v24
	v_lshlrev_b32_e32 v4, 11, v25
	v_mov_b32_e32 v5, v193
	v_lshl_add_u64 v[4:5], v[18:19], 0, v[4:5]
	global_load_dwordx4 v[4:7], v[4:5], off nt
	v_or_b32_e32 v26, 16, v24
	v_lshlrev_b32_e32 v8, 11, v26
	v_mov_b32_e32 v9, v193
	v_lshl_add_u64 v[8:9], v[18:19], 0, v[8:9]
	global_load_dwordx4 v[8:11], v[8:9], off nt
	v_add_u32_e32 v27, s4, v16
	v_lshl_add_u32 v12, v24, 7, v27
	ds_read_b128 v[12:15], v12 offset:51200
	v_lshl_add_u64 v[20:21], s[2:3], 0, v[16:17]
	v_or_b32_e32 v28, 24, v24
	s_waitcnt lgkmcnt(0)
	v_lshlrev_b32_e32 v16, 16, v12
	v_and_b32_e32 v17, 0xffff0000, v12
	v_lshlrev_b32_e32 v12, 16, v13
	v_and_b32_e32 v13, 0xffff0000, v13
	s_waitcnt vmcnt(2)
	v_lshlrev_b32_e32 v22, 16, v0
	v_and_b32_e32 v23, 0xffff0000, v0
	v_pk_mul_f32 v[16:17], v[16:17], v[22:23]
	v_lshlrev_b32_e32 v22, 16, v2
	v_cvt_pk_bf16_f32 v0, v16, v17
	v_lshlrev_b32_e32 v16, 16, v1
	v_and_b32_e32 v17, 0xffff0000, v1
	v_pk_mul_f32 v[12:13], v[12:13], v[16:17]
	v_lshlrev_b32_e32 v16, 11, v28
	v_mov_b32_e32 v17, v193
	v_lshl_add_u64 v[16:17], v[18:19], 0, v[16:17]
	global_load_dwordx4 v[16:19], v[16:17], off nt
	v_cvt_pk_bf16_f32 v1, v12, v13
	v_lshlrev_b32_e32 v12, 16, v14
	v_and_b32_e32 v13, 0xffff0000, v14
	v_and_b32_e32 v23, 0xffff0000, v2
	v_pk_mul_f32 v[12:13], v[12:13], v[22:23]
	v_lshlrev_b32_e32 v14, 16, v3
	v_cvt_pk_bf16_f32 v2, v12, v13
	v_lshlrev_b32_e32 v12, 16, v15
	v_and_b32_e32 v13, 0xffff0000, v15
	v_and_b32_e32 v15, 0xffff0000, v3
	v_pk_mul_f32 v[12:13], v[12:13], v[14:15]
	v_lshlrev_b32_e32 v22, 12, v24
	v_cvt_pk_bf16_f32 v3, v12, v13
	v_lshl_add_u32 v12, v25, 7, v27
	ds_read_b128 v[12:15], v12 offset:51200
	v_mov_b32_e32 v23, v193
	v_lshl_add_u64 v[22:23], v[20:21], 0, v[22:23]
	global_store_dwordx4 v[22:23], v[0:3], off
	s_waitcnt lgkmcnt(0)
	s_nop 0
	v_lshlrev_b32_e32 v0, 16, v12
	v_and_b32_e32 v1, 0xffff0000, v12
	s_waitcnt vmcnt(3)
	v_lshlrev_b32_e32 v2, 16, v4
	v_and_b32_e32 v3, 0xffff0000, v4
	v_pk_mul_f32 v[0:1], v[0:1], v[2:3]
	v_lshlrev_b32_e32 v2, 16, v13
	v_and_b32_e32 v3, 0xffff0000, v13
	v_lshlrev_b32_e32 v4, 16, v5
	v_and_b32_e32 v5, 0xffff0000, v5
	v_pk_mul_f32 v[2:3], v[2:3], v[4:5]
	v_cvt_pk_bf16_f32 v0, v0, v1
	v_cvt_pk_bf16_f32 v1, v2, v3
	v_lshlrev_b32_e32 v2, 16, v14
	v_and_b32_e32 v3, 0xffff0000, v14
	v_lshlrev_b32_e32 v4, 16, v6
	v_and_b32_e32 v5, 0xffff0000, v6
	v_pk_mul_f32 v[2:3], v[2:3], v[4:5]
	v_lshlrev_b32_e32 v4, 16, v15
	v_and_b32_e32 v5, 0xffff0000, v15
	v_lshlrev_b32_e32 v6, 16, v7
	v_and_b32_e32 v7, 0xffff0000, v7
	v_pk_mul_f32 v[4:5], v[4:5], v[6:7]
	v_cvt_pk_bf16_f32 v2, v2, v3
	v_cvt_pk_bf16_f32 v3, v4, v5
	v_lshl_add_u32 v4, v26, 7, v27
	ds_read_b128 v[4:7], v4 offset:51200
	v_lshlrev_b32_e32 v12, 12, v25
	v_mov_b32_e32 v13, v193
	v_lshl_add_u64 v[12:13], v[20:21], 0, v[12:13]
	global_store_dwordx4 v[12:13], v[0:3], off
	s_waitcnt lgkmcnt(0)
	s_nop 0
	v_lshlrev_b32_e32 v0, 16, v4
	v_and_b32_e32 v1, 0xffff0000, v4
	s_waitcnt vmcnt(3)
	v_lshlrev_b32_e32 v2, 16, v8
	v_and_b32_e32 v3, 0xffff0000, v8
	v_pk_mul_f32 v[0:1], v[0:1], v[2:3]
	v_lshlrev_b32_e32 v2, 16, v5
	v_and_b32_e32 v3, 0xffff0000, v5
	v_lshlrev_b32_e32 v4, 16, v9
	v_and_b32_e32 v5, 0xffff0000, v9
	v_pk_mul_f32 v[2:3], v[2:3], v[4:5]
	v_cvt_pk_bf16_f32 v0, v0, v1
	v_cvt_pk_bf16_f32 v1, v2, v3
	v_lshlrev_b32_e32 v2, 16, v6
	v_and_b32_e32 v3, 0xffff0000, v6
	v_lshlrev_b32_e32 v4, 16, v10
	v_and_b32_e32 v5, 0xffff0000, v10
	v_pk_mul_f32 v[2:3], v[2:3], v[4:5]
	v_lshlrev_b32_e32 v4, 16, v7
	v_and_b32_e32 v5, 0xffff0000, v7
	v_lshlrev_b32_e32 v6, 16, v11
	v_and_b32_e32 v7, 0xffff0000, v11
	v_pk_mul_f32 v[4:5], v[4:5], v[6:7]
	v_cvt_pk_bf16_f32 v2, v2, v3
	v_cvt_pk_bf16_f32 v3, v4, v5
	v_lshl_add_u32 v4, v28, 7, v27
	ds_read_b128 v[4:7], v4 offset:51200
	v_lshlrev_b32_e32 v8, 12, v26
	v_mov_b32_e32 v9, v193
	v_lshl_add_u64 v[8:9], v[20:21], 0, v[8:9]
	global_store_dwordx4 v[8:9], v[0:3], off
	s_waitcnt lgkmcnt(0)
	s_nop 0
	v_lshlrev_b32_e32 v0, 16, v4
	v_and_b32_e32 v1, 0xffff0000, v4
	s_waitcnt vmcnt(3)
	v_lshlrev_b32_e32 v2, 16, v16
	v_and_b32_e32 v3, 0xffff0000, v16
	v_pk_mul_f32 v[0:1], v[0:1], v[2:3]
	v_lshlrev_b32_e32 v2, 16, v5
	v_and_b32_e32 v3, 0xffff0000, v5
	v_lshlrev_b32_e32 v4, 16, v17
	v_and_b32_e32 v5, 0xffff0000, v17
	v_pk_mul_f32 v[2:3], v[2:3], v[4:5]
	v_cvt_pk_bf16_f32 v0, v0, v1
	v_cvt_pk_bf16_f32 v1, v2, v3
	v_lshlrev_b32_e32 v2, 16, v6
	v_and_b32_e32 v3, 0xffff0000, v6
	v_lshlrev_b32_e32 v4, 16, v18
	v_and_b32_e32 v5, 0xffff0000, v18
	v_pk_mul_f32 v[2:3], v[2:3], v[4:5]
	v_lshlrev_b32_e32 v4, 16, v7
	v_and_b32_e32 v5, 0xffff0000, v7
	v_lshlrev_b32_e32 v6, 16, v19
	v_and_b32_e32 v7, 0xffff0000, v19
	v_pk_mul_f32 v[4:5], v[4:5], v[6:7]
	v_cvt_pk_bf16_f32 v2, v2, v3
	v_cvt_pk_bf16_f32 v3, v4, v5
	v_lshlrev_b32_e32 v4, 12, v28
	v_mov_b32_e32 v5, v193
	v_lshl_add_u64 v[4:5], v[20:21], 0, v[4:5]
	global_store_dwordx4 v[4:5], v[0:3], off
	s_cmp_lg_u32 s13, 0
	s_cbranch_scc1 .Ltk_skip1
	s_waitcnt vmcnt(4)
	v_readfirstlane_b32 s4, v96
	s_nop 3
	s_add_i32 s4, s4, s65
	s_mov_b64 s[6:7], exec
	s_mov_b64 exec, 1
	v_mov_b32_e32 v96, s4
	v_mov_b32_e32 v97, s68
	ds_write_b32 v97, v96
	s_mov_b64 exec, s[6:7]
